# GEMM K-loops: first iteration peeled with literal-0 SrcC on each accumulator's first MFMA, so the 128-register accumulator zeroing per tile is gone
# baseline (speedup 1.0000x reference)
.LBB0_172:
	v_mov_b64_e32 v[0:1], 0x1080
	s_ashr_i32 s57, s56, 31
	v_cmp_lt_i64_e32 vcc, s[58:59], v[0:1]
	s_lshl_b64 s[58:59], s[56:57], 20
	v_readlane_b32 s34, v255, 26
	v_readlane_b32 s35, v255, 27
	s_add_u32 s58, s34, s58
	s_addc_u32 s59, s35, s59
	s_and_b64 s[60:61], vcc, exec
	s_cselect_b32 s57, s59, s63
	s_cselect_b32 s71, s58, s62
	s_ashr_i32 s55, s54, 31
	s_lshl_b64 s[60:61], s[54:55], 20
	s_add_u32 s60, s33, s60
	s_addc_u32 s61, s37, s61
	s_and_b64 s[66:67], vcc, exec
	s_cselect_b32 s55, s61, s65
	s_cselect_b32 s80, s60, s64
	s_add_u32 s81, s64, 0x100
	s_addc_u32 s82, s65, 0
	s_mov_b32 s83, -2
	s_add_u32 s64, s62, 0x100
	s_addc_u32 s65, s63, 0
	s_add_i32 s34, 0, 0x10000
	v_add_u32_e32 v108, s34, v196
	ds_read_b128 v[96:99], v108
	ds_read_b128 v[100:103], v108 offset:1024
	ds_read_b128 v[104:107], v108 offset:2048
	ds_read_b128 v[158:161], v108 offset:3072
	s_cmp_eq_u32 s83, 28
	s_cselect_b32 s69, s57, s65
	s_cselect_b32 s68, s71, s64
	s_cselect_b32 s67, s55, s82
	s_cselect_b32 s66, s80, s81
	v_lshl_add_u64 v[108:109], s[62:63], 0, v[154:155]
	s_add_i32 m0, s44, 0xc000
	ds_read_b128 v[162:165], v207
	ds_read_b128 v[166:169], v207 offset:1024
	ds_read_b128 v[170:173], v207 offset:2048
	ds_read_b128 v[180:183], v207 offset:3072
	ds_read_b128 v[184:187], v207 offset:4096
	ds_read_b128 v[188:191], v207 offset:5120
	ds_read_b128 v[192:195], v207 offset:6144
	ds_read_b128 v[198:201], v207 offset:7168
	global_load_lds_dwordx4 v[108:109], off
	v_lshl_add_u64 v[108:109], s[62:63], 0, v[156:157]
	s_add_i32 m0, s44, 0xe000
	s_nop 0
	global_load_lds_dwordx4 v[108:109], off
	s_waitcnt lgkmcnt(8)
	s_barrier
	s_waitcnt lgkmcnt(0)
	v_mfma_f32_16x16x32_bf16 v[138:141], v[96:99], v[162:165], 0
	v_mfma_f32_16x16x32_bf16 v[60:63], v[104:107], v[162:165], 0
	v_mfma_f32_16x16x32_bf16 v[134:137], v[96:99], v[170:173], 0
	v_mfma_f32_16x16x32_bf16 v[56:59], v[104:107], v[170:173], 0
	v_mfma_f32_16x16x32_bf16 v[130:133], v[96:99], v[184:187], 0
	v_mfma_f32_16x16x32_bf16 v[52:55], v[104:107], v[184:187], 0
	v_mfma_f32_16x16x32_bf16 v[126:129], v[96:99], v[192:195], 0
	v_mfma_f32_16x16x32_bf16 v[48:51], v[104:107], v[192:195], 0
	v_mfma_f32_16x16x32_bf16 v[138:141], v[100:103], v[166:169], v[138:141]
	v_mfma_f32_16x16x32_bf16 v[60:63], v[158:161], v[166:169], v[60:63]
	v_mfma_f32_16x16x32_bf16 v[134:137], v[100:103], v[180:183], v[134:137]
	v_mfma_f32_16x16x32_bf16 v[56:59], v[158:161], v[180:183], v[56:59]
	v_mfma_f32_16x16x32_bf16 v[130:133], v[100:103], v[188:191], v[130:133]
	v_mfma_f32_16x16x32_bf16 v[52:55], v[158:161], v[188:191], v[52:55]
	v_mfma_f32_16x16x32_bf16 v[126:129], v[100:103], v[198:201], v[126:129]
	v_mfma_f32_16x16x32_bf16 v[48:51], v[158:161], v[198:201], v[48:51]
	s_barrier
	s_add_i32 s35, 0, 0x14000
	s_add_i32 s34, s34, s39
	v_add_u32_e32 v108, s35, v196
	v_lshl_add_u64 v[174:175], s[66:67], 0, v[146:147]
	s_mov_b32 m0, s34
	ds_read_b128 v[208:211], v108
	ds_read_b128 v[212:215], v108 offset:1024
	ds_read_b128 v[216:219], v108 offset:2048
	ds_read_b128 v[220:223], v108 offset:3072
	global_load_lds_dwordx4 v[174:175], off
	v_lshl_add_u64 v[224:225], s[66:67], 0, v[142:143]
	s_add_i32 m0, s34, 0x2000
	s_nop 0
	global_load_lds_dwordx4 v[224:225], off
	s_barrier
	s_waitcnt lgkmcnt(0)
	v_mfma_f32_16x16x32_bf16 v[122:125], v[208:211], v[162:165], 0
	v_mfma_f32_16x16x32_bf16 v[44:47], v[216:219], v[162:165], 0
	v_mfma_f32_16x16x32_bf16 v[114:117], v[208:211], v[170:173], 0
	v_mfma_f32_16x16x32_bf16 v[36:39], v[216:219], v[170:173], 0
	v_mfma_f32_16x16x32_bf16 v[118:121], v[208:211], v[184:187], 0
	v_mfma_f32_16x16x32_bf16 v[40:43], v[216:219], v[184:187], 0
	v_mfma_f32_16x16x32_bf16 v[108:111], v[208:211], v[192:195], 0
	v_mfma_f32_16x16x32_bf16 v[32:35], v[216:219], v[192:195], 0
	v_mfma_f32_16x16x32_bf16 v[122:125], v[212:215], v[166:169], v[122:125]
	v_mfma_f32_16x16x32_bf16 v[44:47], v[220:223], v[166:169], v[44:47]
	v_mfma_f32_16x16x32_bf16 v[114:117], v[212:215], v[180:183], v[114:117]
	v_mfma_f32_16x16x32_bf16 v[36:39], v[220:223], v[180:183], v[36:39]
	v_mfma_f32_16x16x32_bf16 v[118:121], v[212:215], v[188:191], v[118:121]
	v_mfma_f32_16x16x32_bf16 v[40:43], v[220:223], v[188:191], v[40:43]
	v_mfma_f32_16x16x32_bf16 v[108:111], v[212:215], v[198:201], v[108:111]
	v_mfma_f32_16x16x32_bf16 v[32:35], v[220:223], v[198:201], v[32:35]
	s_mov_b32 m0, s44
	v_lshl_add_u64 v[226:227], s[68:69], 0, v[148:149]
	s_barrier
	ds_read_b128 v[162:165], v207 offset:16384
	ds_read_b128 v[166:169], v207 offset:17408
	ds_read_b128 v[170:173], v207 offset:18432
	ds_read_b128 v[180:183], v207 offset:19456
	ds_read_b128 v[184:187], v207 offset:20480
	ds_read_b128 v[188:191], v207 offset:21504
	ds_read_b128 v[192:195], v207 offset:22528
	ds_read_b128 v[198:201], v207 offset:23552
	global_load_lds_dwordx4 v[226:227], off
	v_lshl_add_u64 v[228:229], s[68:69], 0, v[144:145]
	s_mov_b32 m0, s72
	s_nop 0
	global_load_lds_dwordx4 v[228:229], off
	s_barrier
	s_waitcnt lgkmcnt(0)
	v_mfma_f32_16x16x32_bf16 v[92:95], v[96:99], v[162:165], 0
	v_mfma_f32_16x16x32_bf16 v[28:31], v[104:107], v[162:165], 0
	v_mfma_f32_16x16x32_bf16 v[88:91], v[96:99], v[170:173], 0
	v_mfma_f32_16x16x32_bf16 v[24:27], v[104:107], v[170:173], 0
	v_mfma_f32_16x16x32_bf16 v[84:87], v[96:99], v[184:187], 0
	v_mfma_f32_16x16x32_bf16 v[20:23], v[104:107], v[184:187], 0
	v_mfma_f32_16x16x32_bf16 v[80:83], v[96:99], v[192:195], 0
	v_mfma_f32_16x16x32_bf16 v[16:19], v[104:107], v[192:195], 0
	v_mfma_f32_16x16x32_bf16 v[92:95], v[100:103], v[166:169], v[92:95]
	v_mfma_f32_16x16x32_bf16 v[28:31], v[158:161], v[166:169], v[28:31]
	v_mfma_f32_16x16x32_bf16 v[88:91], v[100:103], v[180:183], v[88:91]
	v_mfma_f32_16x16x32_bf16 v[24:27], v[158:161], v[180:183], v[24:27]
	v_mfma_f32_16x16x32_bf16 v[84:87], v[100:103], v[188:191], v[84:87]
	v_mfma_f32_16x16x32_bf16 v[20:23], v[158:161], v[188:191], v[20:23]
	v_mfma_f32_16x16x32_bf16 v[80:83], v[100:103], v[198:201], v[80:83]
	v_mfma_f32_16x16x32_bf16 v[16:19], v[158:161], v[198:201], v[16:19]
	s_barrier
	s_add_u32 s62, s66, 0x80000
	s_addc_u32 s63, s67, 0
	s_add_i32 s34, s35, s39
	v_lshl_add_u64 v[96:97], s[62:63], 0, v[146:147]
	s_mov_b32 m0, s34
	s_nop 0
	global_load_lds_dwordx4 v[96:97], off
	v_lshl_add_u64 v[96:97], s[62:63], 0, v[142:143]
	s_add_i32 m0, s34, 0x2000
	s_nop 0
	global_load_lds_dwordx4 v[96:97], off
	s_waitcnt vmcnt(6)
	s_barrier
	v_mfma_f32_16x16x32_bf16 v[76:79], v[208:211], v[162:165], 0
	v_mfma_f32_16x16x32_bf16 v[12:15], v[216:219], v[162:165], 0
	v_mfma_f32_16x16x32_bf16 v[68:71], v[208:211], v[170:173], 0
	v_mfma_f32_16x16x32_bf16 v[4:7], v[216:219], v[170:173], 0
	v_mfma_f32_16x16x32_bf16 v[72:75], v[208:211], v[184:187], 0
	v_mfma_f32_16x16x32_bf16 v[8:11], v[216:219], v[184:187], 0
	v_mfma_f32_16x16x32_bf16 v[64:67], v[208:211], v[192:195], 0
	v_mfma_f32_16x16x32_bf16 v[0:3], v[216:219], v[192:195], 0
	v_mfma_f32_16x16x32_bf16 v[76:79], v[212:215], v[166:169], v[76:79]
	v_mfma_f32_16x16x32_bf16 v[12:15], v[220:223], v[166:169], v[12:15]
	v_mfma_f32_16x16x32_bf16 v[68:71], v[212:215], v[180:183], v[68:71]
	v_mfma_f32_16x16x32_bf16 v[4:7], v[220:223], v[180:183], v[4:7]
	v_mfma_f32_16x16x32_bf16 v[72:75], v[212:215], v[188:191], v[72:75]
	v_mfma_f32_16x16x32_bf16 v[8:11], v[220:223], v[188:191], v[8:11]
	v_mfma_f32_16x16x32_bf16 v[64:67], v[212:215], v[198:201], v[64:67]
	v_mfma_f32_16x16x32_bf16 v[0:3], v[220:223], v[198:201], v[0:3]
	s_add_i32 s34, 0, 0x18000
	v_add_u32_e32 v112, s34, v196
	s_barrier
	ds_read_b128 v[96:99], v112
	ds_read_b128 v[100:103], v112 offset:1024
	ds_read_b128 v[104:107], v112 offset:2048
	ds_read_b128 v[158:161], v112 offset:3072
	s_add_u32 s62, s68, 0x80000
	s_addc_u32 s63, s69, 0
	s_mov_b32 m0, s73
	v_lshl_add_u64 v[112:113], s[62:63], 0, v[148:149]
	ds_read_b128 v[162:165], v207 offset:32768
	ds_read_b128 v[166:169], v207 offset:33792
	ds_read_b128 v[170:173], v207 offset:34816
	ds_read_b128 v[180:183], v207 offset:35840
	ds_read_b128 v[184:187], v207 offset:36864
	ds_read_b128 v[188:191], v207 offset:37888
	ds_read_b128 v[192:195], v207 offset:38912
	ds_read_b128 v[198:201], v207 offset:39936
	global_load_lds_dwordx4 v[112:113], off
	v_lshl_add_u64 v[112:113], s[62:63], 0, v[144:145]
	s_mov_b32 m0, s74
	s_nop 0
	global_load_lds_dwordx4 v[112:113], off
	s_waitcnt lgkmcnt(8)
	s_barrier
	s_waitcnt lgkmcnt(0)
	v_mfma_f32_16x16x32_bf16 v[138:141], v[96:99], v[162:165], v[138:141]
	v_mfma_f32_16x16x32_bf16 v[60:63], v[104:107], v[162:165], v[60:63]
	v_mfma_f32_16x16x32_bf16 v[134:137], v[96:99], v[170:173], v[134:137]
	v_mfma_f32_16x16x32_bf16 v[56:59], v[104:107], v[170:173], v[56:59]
	v_mfma_f32_16x16x32_bf16 v[130:133], v[96:99], v[184:187], v[130:133]
	v_mfma_f32_16x16x32_bf16 v[52:55], v[104:107], v[184:187], v[52:55]
	v_mfma_f32_16x16x32_bf16 v[126:129], v[96:99], v[192:195], v[126:129]
	v_mfma_f32_16x16x32_bf16 v[48:51], v[104:107], v[192:195], v[48:51]
	v_mfma_f32_16x16x32_bf16 v[138:141], v[100:103], v[166:169], v[138:141]
	v_mfma_f32_16x16x32_bf16 v[60:63], v[158:161], v[166:169], v[60:63]
	v_mfma_f32_16x16x32_bf16 v[134:137], v[100:103], v[180:183], v[134:137]
	v_mfma_f32_16x16x32_bf16 v[56:59], v[158:161], v[180:183], v[56:59]
	v_mfma_f32_16x16x32_bf16 v[130:133], v[100:103], v[188:191], v[130:133]
	v_mfma_f32_16x16x32_bf16 v[52:55], v[158:161], v[188:191], v[52:55]
	v_mfma_f32_16x16x32_bf16 v[126:129], v[100:103], v[198:201], v[126:129]
	v_mfma_f32_16x16x32_bf16 v[48:51], v[158:161], v[198:201], v[48:51]
	s_barrier
	s_add_i32 s35, 0, 0x1c000
	v_add_u32_e32 v112, s35, v196
	s_add_i32 s34, s34, s39
	ds_read_b128 v[208:211], v112
	ds_read_b128 v[212:215], v112 offset:1024
	ds_read_b128 v[216:219], v112 offset:2048
	ds_read_b128 v[220:223], v112 offset:3072
	v_lshl_add_u64 v[112:113], v[174:175], 0, s[40:41]
	s_mov_b32 m0, s34
	s_nop 0
	global_load_lds_dwordx4 v[112:113], off
	v_lshl_add_u64 v[112:113], v[224:225], 0, s[40:41]
	s_add_i32 m0, s34, 0x2000
	s_nop 0
	global_load_lds_dwordx4 v[112:113], off
	s_barrier
	s_waitcnt lgkmcnt(0)
	v_mfma_f32_16x16x32_bf16 v[122:125], v[208:211], v[162:165], v[122:125]
	v_mfma_f32_16x16x32_bf16 v[44:47], v[216:219], v[162:165], v[44:47]
	v_mfma_f32_16x16x32_bf16 v[112:115], v[208:211], v[170:173], v[114:117]
	v_mfma_f32_16x16x32_bf16 v[36:39], v[216:219], v[170:173], v[36:39]
	v_mfma_f32_16x16x32_bf16 v[118:121], v[208:211], v[184:187], v[118:121]
	v_mfma_f32_16x16x32_bf16 v[40:43], v[216:219], v[184:187], v[40:43]
	v_mfma_f32_16x16x32_bf16 v[108:111], v[208:211], v[192:195], v[108:111]
	v_mfma_f32_16x16x32_bf16 v[32:35], v[216:219], v[192:195], v[32:35]
	v_mfma_f32_16x16x32_bf16 v[122:125], v[212:215], v[166:169], v[122:125]
	v_mfma_f32_16x16x32_bf16 v[44:47], v[220:223], v[166:169], v[44:47]
	v_mfma_f32_16x16x32_bf16 v[114:117], v[212:215], v[180:183], v[112:115]
	v_mfma_f32_16x16x32_bf16 v[36:39], v[220:223], v[180:183], v[36:39]
	v_mfma_f32_16x16x32_bf16 v[118:121], v[212:215], v[188:191], v[118:121]
	v_mfma_f32_16x16x32_bf16 v[40:43], v[220:223], v[188:191], v[40:43]
	v_mfma_f32_16x16x32_bf16 v[110:113], v[212:215], v[198:201], v[108:111]
	v_mfma_f32_16x16x32_bf16 v[32:35], v[220:223], v[198:201], v[32:35]
	s_barrier
	s_mov_b32 m0, s76
	v_lshl_add_u64 v[108:109], v[226:227], 0, s[40:41]
	ds_read_b128 v[162:165], v207 offset:49152
	ds_read_b128 v[166:169], v207 offset:50176
	ds_read_b128 v[170:173], v207 offset:51200
	ds_read_b128 v[180:183], v207 offset:52224
	ds_read_b128 v[184:187], v207 offset:53248
	ds_read_b128 v[188:191], v207 offset:54272
	ds_read_b128 v[192:195], v207 offset:55296
	ds_read_b128 v[198:201], v207 offset:56320
	global_load_lds_dwordx4 v[108:109], off
	v_lshl_add_u64 v[108:109], v[228:229], 0, s[40:41]
	s_mov_b32 m0, s77
	s_nop 0
	global_load_lds_dwordx4 v[108:109], off
	s_barrier
	s_waitcnt lgkmcnt(0)
	v_mfma_f32_16x16x32_bf16 v[92:95], v[96:99], v[162:165], v[92:95]
	v_mfma_f32_16x16x32_bf16 v[28:31], v[104:107], v[162:165], v[28:31]
	v_mfma_f32_16x16x32_bf16 v[88:91], v[96:99], v[170:173], v[88:91]
	v_mfma_f32_16x16x32_bf16 v[24:27], v[104:107], v[170:173], v[24:27]
	v_mfma_f32_16x16x32_bf16 v[84:87], v[96:99], v[184:187], v[84:87]
	v_mfma_f32_16x16x32_bf16 v[20:23], v[104:107], v[184:187], v[20:23]
	v_mfma_f32_16x16x32_bf16 v[80:83], v[96:99], v[192:195], v[80:83]
	v_mfma_f32_16x16x32_bf16 v[16:19], v[104:107], v[192:195], v[16:19]
	v_mfma_f32_16x16x32_bf16 v[92:95], v[100:103], v[166:169], v[92:95]
	v_mfma_f32_16x16x32_bf16 v[28:31], v[158:161], v[166:169], v[28:31]
	v_mfma_f32_16x16x32_bf16 v[88:91], v[100:103], v[180:183], v[88:91]
	v_mfma_f32_16x16x32_bf16 v[24:27], v[158:161], v[180:183], v[24:27]
	v_mfma_f32_16x16x32_bf16 v[84:87], v[100:103], v[188:191], v[84:87]
	v_mfma_f32_16x16x32_bf16 v[20:23], v[158:161], v[188:191], v[20:23]
	v_mfma_f32_16x16x32_bf16 v[80:83], v[100:103], v[198:201], v[80:83]
	v_mfma_f32_16x16x32_bf16 v[16:19], v[158:161], v[198:201], v[16:19]
	s_barrier
	s_add_u32 s62, s66, 0x80080
	s_addc_u32 s63, s67, 0
	s_add_i32 s34, s35, s39
	v_lshl_add_u64 v[96:97], s[62:63], 0, v[146:147]
	s_mov_b32 m0, s34
	s_nop 0
	global_load_lds_dwordx4 v[96:97], off
	v_lshl_add_u64 v[96:97], s[62:63], 0, v[142:143]
	s_add_i32 m0, s34, 0x2000
	s_nop 0
	global_load_lds_dwordx4 v[96:97], off
	s_waitcnt vmcnt(6)
	s_barrier
	v_mfma_f32_16x16x32_bf16 v[76:79], v[208:211], v[162:165], v[76:79]
	v_mfma_f32_16x16x32_bf16 v[12:15], v[216:219], v[162:165], v[12:15]
	v_mfma_f32_16x16x32_bf16 v[68:71], v[208:211], v[170:173], v[68:71]
	v_mfma_f32_16x16x32_bf16 v[4:7], v[216:219], v[170:173], v[4:7]
	v_mfma_f32_16x16x32_bf16 v[72:75], v[208:211], v[184:187], v[72:75]
	v_mfma_f32_16x16x32_bf16 v[8:11], v[216:219], v[184:187], v[8:11]
	v_mfma_f32_16x16x32_bf16 v[64:67], v[208:211], v[192:195], v[64:67]
	v_mfma_f32_16x16x32_bf16 v[0:3], v[216:219], v[192:195], v[0:3]
	v_mfma_f32_16x16x32_bf16 v[76:79], v[212:215], v[166:169], v[76:79]
	v_mfma_f32_16x16x32_bf16 v[12:15], v[220:223], v[166:169], v[12:15]
	v_mfma_f32_16x16x32_bf16 v[68:71], v[212:215], v[180:183], v[68:71]
	v_mfma_f32_16x16x32_bf16 v[4:7], v[220:223], v[180:183], v[4:7]
	v_mfma_f32_16x16x32_bf16 v[72:75], v[212:215], v[188:191], v[72:75]
	v_mfma_f32_16x16x32_bf16 v[8:11], v[220:223], v[188:191], v[8:11]
	v_mfma_f32_16x16x32_bf16 v[64:67], v[212:215], v[198:201], v[64:67]
	v_mfma_f32_16x16x32_bf16 v[0:3], v[220:223], v[198:201], v[0:3]
	s_add_i32 s83, s83, 2
	s_add_u32 s81, s81, 0x100
	s_addc_u32 s82, s82, 0
	s_cmp_gt_u32 s83, 29
	s_mov_b64 s[62:63], s[64:65]
	s_barrier

.LBB0_263:
	s_add_u32 s59, s24, 0x100
	s_addc_u32 s60, s25, 0
	s_add_u32 s8, s26, 0x80
	s_addc_u32 s9, s27, 0
	s_mov_b32 s24, 0
	s_add_i32 s61, s24, 2
	s_add_u32 s26, s8, 0x80
	s_addc_u32 s25, s9, 0
	s_add_i32 s29, 0, 0x10000
	v_add_u32_e32 v140, s29, v193
	ds_read_b128 v[128:131], v140
	ds_read_b128 v[132:135], v140 offset:1024
	ds_read_b128 v[136:139], v140 offset:2048
	ds_read_b128 v[140:143], v140 offset:3072
	s_cmp_eq_u32 s47, s24
	s_cselect_b32 s24, s20, s26
	s_cselect_b32 s25, s21, s25
	s_cselect_b32 s27, s11, s60
	s_cselect_b32 s26, s10, s59
	v_lshl_add_u64 v[180:181], s[8:9], 0, v[174:175]
	s_add_i32 m0, s33, 0xc000
	ds_read_b128 v[144:147], v195
	ds_read_b128 v[148:151], v195 offset:1024
	ds_read_b128 v[152:155], v195 offset:2048
	ds_read_b128 v[156:159], v195 offset:3072
	ds_read_b128 v[160:163], v195 offset:4096
	ds_read_b128 v[164:167], v195 offset:5120
	ds_read_b128 v[184:187], v195 offset:6144
	ds_read_b128 v[188:191], v195 offset:7168
	global_load_lds_dwordx4 v[180:181], off
	v_lshl_add_u64 v[180:181], s[8:9], 0, v[182:183]
	s_add_i32 m0, s33, 0xe000
	s_nop 0
	global_load_lds_dwordx4 v[180:181], off
	s_waitcnt lgkmcnt(8)
	s_barrier
	s_waitcnt lgkmcnt(0)
	v_mfma_f32_16x16x32_bf16 v[124:127], v[128:131], v[144:147], 0
	v_mfma_f32_16x16x32_bf16 v[120:123], v[136:139], v[144:147], 0
	v_mfma_f32_16x16x32_bf16 v[108:111], v[128:131], v[152:155], 0
	v_mfma_f32_16x16x32_bf16 v[104:107], v[136:139], v[152:155], 0
	v_mfma_f32_16x16x32_bf16 v[92:95], v[128:131], v[160:163], 0
	v_mfma_f32_16x16x32_bf16 v[88:91], v[136:139], v[160:163], 0
	v_mfma_f32_16x16x32_bf16 v[76:79], v[128:131], v[184:187], 0
	v_mfma_f32_16x16x32_bf16 v[72:75], v[136:139], v[184:187], 0
	v_mfma_f32_16x16x32_bf16 v[124:127], v[132:135], v[148:151], v[124:127]
	v_mfma_f32_16x16x32_bf16 v[120:123], v[140:143], v[148:151], v[120:123]
	v_mfma_f32_16x16x32_bf16 v[108:111], v[132:135], v[156:159], v[108:111]
	v_mfma_f32_16x16x32_bf16 v[104:107], v[140:143], v[156:159], v[104:107]
	v_mfma_f32_16x16x32_bf16 v[92:95], v[132:135], v[164:167], v[92:95]
	v_mfma_f32_16x16x32_bf16 v[88:91], v[140:143], v[164:167], v[88:91]
	v_mfma_f32_16x16x32_bf16 v[76:79], v[132:135], v[188:191], v[76:79]
	v_mfma_f32_16x16x32_bf16 v[72:75], v[140:143], v[188:191], v[72:75]
	s_barrier
	s_add_i32 s34, 0, 0x14000
	s_add_i32 s29, s29, s31
	v_add_u32_e32 v178, s34, v193
	v_lshl_add_u64 v[180:181], s[26:27], 0, v[176:177]
	s_mov_b32 m0, s29
	ds_read_b128 v[196:199], v178
	ds_read_b128 v[208:211], v178 offset:1024
	ds_read_b128 v[212:215], v178 offset:2048
	ds_read_b128 v[216:219], v178 offset:3072
	global_load_lds_dwordx4 v[180:181], off
	v_lshl_add_u64 v[200:201], s[26:27], 0, v[168:169]
	s_add_i32 m0, s29, 0x2000
	s_nop 0
	global_load_lds_dwordx4 v[200:201], off
	s_barrier
	s_waitcnt lgkmcnt(0)
	v_mfma_f32_16x16x32_bf16 v[116:119], v[196:199], v[144:147], 0
	v_mfma_f32_16x16x32_bf16 v[112:115], v[212:215], v[144:147], 0
	v_mfma_f32_16x16x32_bf16 v[100:103], v[196:199], v[152:155], 0
	v_mfma_f32_16x16x32_bf16 v[96:99], v[212:215], v[152:155], 0
	v_mfma_f32_16x16x32_bf16 v[84:87], v[196:199], v[160:163], 0
	v_mfma_f32_16x16x32_bf16 v[80:83], v[212:215], v[160:163], 0
	v_mfma_f32_16x16x32_bf16 v[68:71], v[196:199], v[184:187], 0
	v_mfma_f32_16x16x32_bf16 v[64:67], v[212:215], v[184:187], 0
	v_mfma_f32_16x16x32_bf16 v[116:119], v[208:211], v[148:151], v[116:119]
	v_mfma_f32_16x16x32_bf16 v[112:115], v[216:219], v[148:151], v[112:115]
	v_mfma_f32_16x16x32_bf16 v[100:103], v[208:211], v[156:159], v[100:103]
	v_mfma_f32_16x16x32_bf16 v[96:99], v[216:219], v[156:159], v[96:99]
	v_mfma_f32_16x16x32_bf16 v[84:87], v[208:211], v[164:167], v[84:87]
	v_mfma_f32_16x16x32_bf16 v[80:83], v[216:219], v[164:167], v[80:83]
	v_mfma_f32_16x16x32_bf16 v[68:71], v[208:211], v[188:191], v[68:71]
	v_mfma_f32_16x16x32_bf16 v[64:67], v[216:219], v[188:191], v[64:67]
	s_mov_b32 m0, s33
	v_lshl_add_u64 v[220:221], s[24:25], 0, v[172:173]
	s_barrier
	ds_read_b128 v[144:147], v195 offset:16384
	ds_read_b128 v[148:151], v195 offset:17408
	ds_read_b128 v[152:155], v195 offset:18432
	ds_read_b128 v[156:159], v195 offset:19456
	ds_read_b128 v[160:163], v195 offset:20480
	ds_read_b128 v[164:167], v195 offset:21504
	ds_read_b128 v[184:187], v195 offset:22528
	ds_read_b128 v[188:191], v195 offset:23552
	global_load_lds_dwordx4 v[220:221], off
	v_lshl_add_u64 v[222:223], s[24:25], 0, v[170:171]
	s_mov_b32 m0, s37
	s_nop 0
	global_load_lds_dwordx4 v[222:223], off
	s_barrier
	s_waitcnt lgkmcnt(0)
	v_mfma_f32_16x16x32_bf16 v[60:63], v[128:131], v[144:147], 0
	v_mfma_f32_16x16x32_bf16 v[56:59], v[136:139], v[144:147], 0
	v_mfma_f32_16x16x32_bf16 v[44:47], v[128:131], v[152:155], 0
	v_mfma_f32_16x16x32_bf16 v[40:43], v[136:139], v[152:155], 0
	v_mfma_f32_16x16x32_bf16 v[28:31], v[128:131], v[160:163], 0
	v_mfma_f32_16x16x32_bf16 v[24:27], v[136:139], v[160:163], 0
	v_mfma_f32_16x16x32_bf16 v[12:15], v[128:131], v[184:187], 0
	v_mfma_f32_16x16x32_bf16 v[8:11], v[136:139], v[184:187], 0
	v_mfma_f32_16x16x32_bf16 v[60:63], v[132:135], v[148:151], v[60:63]
	v_mfma_f32_16x16x32_bf16 v[56:59], v[140:143], v[148:151], v[56:59]
	v_mfma_f32_16x16x32_bf16 v[44:47], v[132:135], v[156:159], v[44:47]
	v_mfma_f32_16x16x32_bf16 v[40:43], v[140:143], v[156:159], v[40:43]
	v_mfma_f32_16x16x32_bf16 v[28:31], v[132:135], v[164:167], v[28:31]
	v_mfma_f32_16x16x32_bf16 v[24:27], v[140:143], v[164:167], v[24:27]
	v_mfma_f32_16x16x32_bf16 v[12:15], v[132:135], v[188:191], v[12:15]
	v_mfma_f32_16x16x32_bf16 v[8:11], v[140:143], v[188:191], v[8:11]
	s_barrier
	s_add_u32 s26, s26, s44
	s_addc_u32 s27, s27, 0
	s_add_i32 s29, s34, s31
	v_lshl_add_u64 v[224:225], s[26:27], 0, v[176:177]
	s_mov_b32 m0, s29
	v_lshl_add_u64 v[226:227], s[26:27], 0, v[168:169]
	global_load_lds_dwordx4 v[224:225], off
	s_add_i32 m0, s29, 0x2000
	s_nop 0
	global_load_lds_dwordx4 v[226:227], off
	s_waitcnt vmcnt(6)
	s_barrier
	v_mfma_f32_16x16x32_bf16 v[52:55], v[196:199], v[144:147], 0
	v_mfma_f32_16x16x32_bf16 v[48:51], v[212:215], v[144:147], 0
	v_mfma_f32_16x16x32_bf16 v[36:39], v[196:199], v[152:155], 0
	v_mfma_f32_16x16x32_bf16 v[32:35], v[212:215], v[152:155], 0
	v_mfma_f32_16x16x32_bf16 v[20:23], v[196:199], v[160:163], 0
	v_mfma_f32_16x16x32_bf16 v[16:19], v[212:215], v[160:163], 0
	v_mfma_f32_16x16x32_bf16 v[4:7], v[196:199], v[184:187], 0
	v_mfma_f32_16x16x32_bf16 v[0:3], v[212:215], v[184:187], 0
	v_mfma_f32_16x16x32_bf16 v[52:55], v[208:211], v[148:151], v[52:55]
	v_mfma_f32_16x16x32_bf16 v[48:51], v[216:219], v[148:151], v[48:51]
	v_mfma_f32_16x16x32_bf16 v[36:39], v[208:211], v[156:159], v[36:39]
	v_mfma_f32_16x16x32_bf16 v[32:35], v[216:219], v[156:159], v[32:35]
	v_mfma_f32_16x16x32_bf16 v[20:23], v[208:211], v[164:167], v[20:23]
	v_mfma_f32_16x16x32_bf16 v[16:19], v[216:219], v[164:167], v[16:19]
	v_mfma_f32_16x16x32_bf16 v[4:7], v[208:211], v[188:191], v[4:7]
	v_mfma_f32_16x16x32_bf16 v[0:3], v[216:219], v[188:191], v[0:3]
	s_add_i32 s26, 0, 0x18000
	v_add_u32_e32 v140, s26, v193
	s_barrier
	ds_read_b128 v[128:131], v140
	ds_read_b128 v[132:135], v140 offset:1024
	ds_read_b128 v[136:139], v140 offset:2048
	ds_read_b128 v[140:143], v140 offset:3072
	s_add_u32 s24, s24, s44
	s_addc_u32 s25, s25, 0
	s_mov_b32 m0, s38
	v_lshl_add_u64 v[196:197], s[24:25], 0, v[172:173]
	ds_read_b128 v[144:147], v195 offset:32768
	ds_read_b128 v[148:151], v195 offset:33792
	ds_read_b128 v[152:155], v195 offset:34816
	ds_read_b128 v[156:159], v195 offset:35840
	ds_read_b128 v[160:163], v195 offset:36864
	ds_read_b128 v[164:167], v195 offset:37888
	ds_read_b128 v[184:187], v195 offset:38912
	ds_read_b128 v[188:191], v195 offset:39936
	global_load_lds_dwordx4 v[196:197], off
	v_lshl_add_u64 v[196:197], s[24:25], 0, v[170:171]
	s_mov_b32 m0, s39
	s_nop 0
	global_load_lds_dwordx4 v[196:197], off
	s_waitcnt lgkmcnt(8)
	s_barrier
	s_waitcnt lgkmcnt(0)
	v_mfma_f32_16x16x32_bf16 v[124:127], v[128:131], v[144:147], v[124:127]
	v_mfma_f32_16x16x32_bf16 v[120:123], v[136:139], v[144:147], v[120:123]
	v_mfma_f32_16x16x32_bf16 v[108:111], v[128:131], v[152:155], v[108:111]
	v_mfma_f32_16x16x32_bf16 v[104:107], v[136:139], v[152:155], v[104:107]
	v_mfma_f32_16x16x32_bf16 v[92:95], v[128:131], v[160:163], v[92:95]
	v_mfma_f32_16x16x32_bf16 v[88:91], v[136:139], v[160:163], v[88:91]
	v_mfma_f32_16x16x32_bf16 v[76:79], v[128:131], v[184:187], v[76:79]
	v_mfma_f32_16x16x32_bf16 v[72:75], v[136:139], v[184:187], v[72:75]
	v_mfma_f32_16x16x32_bf16 v[124:127], v[132:135], v[148:151], v[124:127]
	v_mfma_f32_16x16x32_bf16 v[120:123], v[140:143], v[148:151], v[120:123]
	v_mfma_f32_16x16x32_bf16 v[108:111], v[132:135], v[156:159], v[108:111]
	v_mfma_f32_16x16x32_bf16 v[104:107], v[140:143], v[156:159], v[104:107]
	v_mfma_f32_16x16x32_bf16 v[92:95], v[132:135], v[164:167], v[92:95]
	v_mfma_f32_16x16x32_bf16 v[88:91], v[140:143], v[164:167], v[88:91]
	v_mfma_f32_16x16x32_bf16 v[76:79], v[132:135], v[188:191], v[76:79]
	v_mfma_f32_16x16x32_bf16 v[72:75], v[140:143], v[188:191], v[72:75]
	s_barrier
	s_add_i32 s24, 0, 0x1c000
	s_add_i32 s25, s26, s31
	v_add_u32_e32 v178, s24, v193
	v_lshl_add_u64 v[180:181], v[180:181], 0, s[40:41]
	s_mov_b32 m0, s25
	ds_read_b128 v[196:199], v178
	ds_read_b128 v[208:211], v178 offset:1024
	ds_read_b128 v[212:215], v178 offset:2048
	ds_read_b128 v[216:219], v178 offset:3072
	global_load_lds_dwordx4 v[180:181], off
	v_lshl_add_u64 v[180:181], v[200:201], 0, s[40:41]
	s_add_i32 m0, s25, 0x2000
	s_nop 0
	global_load_lds_dwordx4 v[180:181], off
	s_barrier
	s_waitcnt lgkmcnt(0)
	v_mfma_f32_16x16x32_bf16 v[116:119], v[196:199], v[144:147], v[116:119]
	v_mfma_f32_16x16x32_bf16 v[112:115], v[212:215], v[144:147], v[112:115]
	v_mfma_f32_16x16x32_bf16 v[100:103], v[196:199], v[152:155], v[100:103]
	v_mfma_f32_16x16x32_bf16 v[96:99], v[212:215], v[152:155], v[96:99]
	v_mfma_f32_16x16x32_bf16 v[84:87], v[196:199], v[160:163], v[84:87]
	v_mfma_f32_16x16x32_bf16 v[80:83], v[212:215], v[160:163], v[80:83]
	v_mfma_f32_16x16x32_bf16 v[68:71], v[196:199], v[184:187], v[68:71]
	v_mfma_f32_16x16x32_bf16 v[64:67], v[212:215], v[184:187], v[64:67]
	v_mfma_f32_16x16x32_bf16 v[116:119], v[208:211], v[148:151], v[116:119]
	v_mfma_f32_16x16x32_bf16 v[112:115], v[216:219], v[148:151], v[112:115]
	v_mfma_f32_16x16x32_bf16 v[100:103], v[208:211], v[156:159], v[100:103]
	v_mfma_f32_16x16x32_bf16 v[96:99], v[216:219], v[156:159], v[96:99]
	v_mfma_f32_16x16x32_bf16 v[84:87], v[208:211], v[164:167], v[84:87]
	v_mfma_f32_16x16x32_bf16 v[80:83], v[216:219], v[164:167], v[80:83]
	v_mfma_f32_16x16x32_bf16 v[68:71], v[208:211], v[188:191], v[68:71]
	v_mfma_f32_16x16x32_bf16 v[64:67], v[216:219], v[188:191], v[64:67]
	s_mov_b32 m0, s43
	v_lshl_add_u64 v[180:181], v[220:221], 0, s[40:41]
	s_barrier
	ds_read_b128 v[144:147], v195 offset:49152
	ds_read_b128 v[148:151], v195 offset:50176
	ds_read_b128 v[152:155], v195 offset:51200
	ds_read_b128 v[156:159], v195 offset:52224
	ds_read_b128 v[160:163], v195 offset:53248
	ds_read_b128 v[164:167], v195 offset:54272
	ds_read_b128 v[184:187], v195 offset:55296
	ds_read_b128 v[188:191], v195 offset:56320
	global_load_lds_dwordx4 v[180:181], off
	v_lshl_add_u64 v[180:181], v[222:223], 0, s[40:41]
	s_mov_b32 m0, s46
	s_nop 0
	global_load_lds_dwordx4 v[180:181], off
	s_barrier
	s_waitcnt lgkmcnt(0)
	v_mfma_f32_16x16x32_bf16 v[60:63], v[128:131], v[144:147], v[60:63]
	v_mfma_f32_16x16x32_bf16 v[56:59], v[136:139], v[144:147], v[56:59]
	v_mfma_f32_16x16x32_bf16 v[44:47], v[128:131], v[152:155], v[44:47]
	v_mfma_f32_16x16x32_bf16 v[40:43], v[136:139], v[152:155], v[40:43]
	v_mfma_f32_16x16x32_bf16 v[28:31], v[128:131], v[160:163], v[28:31]
	v_mfma_f32_16x16x32_bf16 v[24:27], v[136:139], v[160:163], v[24:27]
	v_mfma_f32_16x16x32_bf16 v[12:15], v[128:131], v[184:187], v[12:15]
	v_mfma_f32_16x16x32_bf16 v[8:11], v[136:139], v[184:187], v[8:11]
	v_mfma_f32_16x16x32_bf16 v[60:63], v[132:135], v[148:151], v[60:63]
	v_mfma_f32_16x16x32_bf16 v[56:59], v[140:143], v[148:151], v[56:59]
	v_mfma_f32_16x16x32_bf16 v[44:47], v[132:135], v[156:159], v[44:47]
	v_mfma_f32_16x16x32_bf16 v[40:43], v[140:143], v[156:159], v[40:43]
	v_mfma_f32_16x16x32_bf16 v[28:31], v[132:135], v[164:167], v[28:31]
	v_mfma_f32_16x16x32_bf16 v[24:27], v[140:143], v[164:167], v[24:27]
	v_mfma_f32_16x16x32_bf16 v[12:15], v[132:135], v[188:191], v[12:15]
	v_mfma_f32_16x16x32_bf16 v[8:11], v[140:143], v[188:191], v[8:11]
	s_barrier
	s_add_i32 s24, s24, s31
	v_lshl_add_u64 v[128:129], v[224:225], 0, s[40:41]
	s_mov_b32 m0, s24
	s_nop 0
	global_load_lds_dwordx4 v[128:129], off
	v_lshl_add_u64 v[128:129], v[226:227], 0, s[40:41]
	s_add_i32 m0, s24, 0x2000
	s_nop 0
	global_load_lds_dwordx4 v[128:129], off
	s_waitcnt vmcnt(6)
	s_barrier
	v_mfma_f32_16x16x32_bf16 v[52:55], v[196:199], v[144:147], v[52:55]
	v_mfma_f32_16x16x32_bf16 v[48:51], v[212:215], v[144:147], v[48:51]
	v_mfma_f32_16x16x32_bf16 v[36:39], v[196:199], v[152:155], v[36:39]
	v_mfma_f32_16x16x32_bf16 v[32:35], v[212:215], v[152:155], v[32:35]
	v_mfma_f32_16x16x32_bf16 v[20:23], v[196:199], v[160:163], v[20:23]
	v_mfma_f32_16x16x32_bf16 v[16:19], v[212:215], v[160:163], v[16:19]
	v_mfma_f32_16x16x32_bf16 v[4:7], v[196:199], v[184:187], v[4:7]
	v_mfma_f32_16x16x32_bf16 v[0:3], v[212:215], v[184:187], v[0:3]
	v_mfma_f32_16x16x32_bf16 v[52:55], v[208:211], v[148:151], v[52:55]
	v_mfma_f32_16x16x32_bf16 v[48:51], v[216:219], v[148:151], v[48:51]
	v_mfma_f32_16x16x32_bf16 v[36:39], v[208:211], v[156:159], v[36:39]
	v_mfma_f32_16x16x32_bf16 v[32:35], v[216:219], v[156:159], v[32:35]
	v_mfma_f32_16x16x32_bf16 v[20:23], v[208:211], v[164:167], v[20:23]
	v_mfma_f32_16x16x32_bf16 v[16:19], v[216:219], v[164:167], v[16:19]
	v_mfma_f32_16x16x32_bf16 v[4:7], v[208:211], v[188:191], v[4:7]
	v_mfma_f32_16x16x32_bf16 v[0:3], v[216:219], v[188:191], v[0:3]
	s_add_u32 s59, s59, 0x100
	s_addc_u32 s60, s60, 0
	s_add_u32 s8, s8, 0x100
	s_addc_u32 s9, s9, 0
	s_cmp_ge_u32 s61, s42
	s_mov_b32 s24, s61
	s_barrier

.LBB0_638:
	v_mov_b64_e32 v[0:1], s[4:5]
	s_ashr_i32 s15, s14, 31
	v_cmp_lt_i64_e32 vcc, s[20:21], v[0:1]
	s_lshl_b64 s[20:21], s[14:15], s50
	s_add_u32 s13, s37, s20
	s_addc_u32 s15, s38, s21
	s_and_b64 s[20:21], vcc, exec
	s_cselect_b32 s21, s15, s27
	s_cselect_b32 s20, s13, s26
	s_ashr_i32 s13, s12, 31
	s_lshl_b64 s[24:25], s[12:13], s50
	s_add_u32 s13, s39, s24
	s_addc_u32 s15, s46, s25
	s_and_b64 s[24:25], vcc, exec
	s_cselect_b32 s25, s15, s31
	s_cselect_b32 s24, s13, s30
	s_add_u32 s26, s26, 0x80
	s_addc_u32 s27, s27, 0
	s_add_u32 s13, s30, 0x100
	s_addc_u32 s15, s31, 0
	s_mov_b32 s30, 0
	s_add_i32 s60, s30, 2
	s_add_u32 s29, s26, 0x80
	s_addc_u32 s31, s27, 0
	s_add_i32 s34, 0, 0x10000
	v_add_u32_e32 v156, s34, v141
	ds_read_b128 v[144:147], v156
	ds_read_b128 v[148:151], v156 offset:1024
	ds_read_b128 v[152:155], v156 offset:2048
	ds_read_b128 v[156:159], v156 offset:3072
	s_cmp_eq_u32 s58, s30
	s_cselect_b32 s30, s20, s29
	s_cselect_b32 s31, s21, s31
	s_cselect_b32 s43, s25, s15
	s_cselect_b32 s42, s24, s13
	v_lshl_add_u64 v[196:197], s[26:27], 0, v[136:137]
	s_add_i32 m0, s17, 0xc000
	ds_read_b128 v[160:163], v143
	ds_read_b128 v[164:167], v143 offset:1024
	ds_read_b128 v[168:171], v143 offset:2048
	ds_read_b128 v[172:175], v143 offset:3072
	ds_read_b128 v[180:183], v143 offset:4096
	ds_read_b128 v[184:187], v143 offset:5120
	ds_read_b128 v[188:191], v143 offset:6144
	ds_read_b128 v[192:195], v143 offset:7168
	global_load_lds_dwordx4 v[196:197], off
	v_lshl_add_u64 v[196:197], s[26:27], 0, v[138:139]
	s_add_i32 m0, s17, 0xe000
	s_nop 0
	global_load_lds_dwordx4 v[196:197], off
	s_waitcnt lgkmcnt(8)
	s_barrier
	s_waitcnt lgkmcnt(0)
	v_mfma_f32_16x16x32_bf16 v[124:127], v[144:147], v[160:163], 0
	v_mfma_f32_16x16x32_bf16 v[120:123], v[152:155], v[160:163], 0
	v_mfma_f32_16x16x32_bf16 v[116:119], v[144:147], v[168:171], 0
	v_mfma_f32_16x16x32_bf16 v[112:115], v[152:155], v[168:171], 0
	v_mfma_f32_16x16x32_bf16 v[108:111], v[144:147], v[180:183], 0
	v_mfma_f32_16x16x32_bf16 v[104:107], v[152:155], v[180:183], 0
	v_mfma_f32_16x16x32_bf16 v[100:103], v[144:147], v[188:191], 0
	v_mfma_f32_16x16x32_bf16 v[96:99], v[152:155], v[188:191], 0
	v_mfma_f32_16x16x32_bf16 v[124:127], v[148:151], v[164:167], v[124:127]
	v_mfma_f32_16x16x32_bf16 v[120:123], v[156:159], v[164:167], v[120:123]
	v_mfma_f32_16x16x32_bf16 v[116:119], v[148:151], v[172:175], v[116:119]
	v_mfma_f32_16x16x32_bf16 v[112:115], v[156:159], v[172:175], v[112:115]
	v_mfma_f32_16x16x32_bf16 v[108:111], v[148:151], v[184:187], v[108:111]
	v_mfma_f32_16x16x32_bf16 v[104:107], v[156:159], v[184:187], v[104:107]
	v_mfma_f32_16x16x32_bf16 v[100:103], v[148:151], v[192:195], v[100:103]
	v_mfma_f32_16x16x32_bf16 v[96:99], v[156:159], v[192:195], v[96:99]
	s_barrier
	s_add_i32 s29, 0, 0x14000
	s_add_i32 s34, s34, s48
	v_add_u32_e32 v176, s29, v141
	v_lshl_add_u64 v[200:201], s[42:43], 0, v[130:131]
	s_mov_b32 m0, s34
	ds_read_b128 v[196:199], v176
	ds_read_b128 v[208:211], v176 offset:1024
	ds_read_b128 v[212:215], v176 offset:2048
	ds_read_b128 v[216:219], v176 offset:3072
	global_load_lds_dwordx4 v[200:201], off
	v_lshl_add_u64 v[220:221], s[42:43], 0, v[134:135]
	s_add_i32 m0, s34, 0x2000
	s_nop 0
	global_load_lds_dwordx4 v[220:221], off
	s_barrier
	s_waitcnt lgkmcnt(0)
	v_mfma_f32_16x16x32_bf16 v[72:75], v[196:199], v[160:163], 0
	v_mfma_f32_16x16x32_bf16 v[64:67], v[212:215], v[160:163], 0
	v_mfma_f32_16x16x32_bf16 v[56:59], v[196:199], v[168:171], 0
	v_mfma_f32_16x16x32_bf16 v[48:51], v[212:215], v[168:171], 0
	v_mfma_f32_16x16x32_bf16 v[44:47], v[196:199], v[180:183], 0
	v_mfma_f32_16x16x32_bf16 v[40:43], v[212:215], v[180:183], 0
	v_mfma_f32_16x16x32_bf16 v[36:39], v[196:199], v[188:191], 0
	v_mfma_f32_16x16x32_bf16 v[32:35], v[212:215], v[188:191], 0
	v_mfma_f32_16x16x32_bf16 v[72:75], v[208:211], v[164:167], v[72:75]
	v_mfma_f32_16x16x32_bf16 v[64:67], v[216:219], v[164:167], v[64:67]
	v_mfma_f32_16x16x32_bf16 v[56:59], v[208:211], v[172:175], v[56:59]
	v_mfma_f32_16x16x32_bf16 v[48:51], v[216:219], v[172:175], v[48:51]
	v_mfma_f32_16x16x32_bf16 v[44:47], v[208:211], v[184:187], v[44:47]
	v_mfma_f32_16x16x32_bf16 v[40:43], v[216:219], v[184:187], v[40:43]
	v_mfma_f32_16x16x32_bf16 v[36:39], v[208:211], v[192:195], v[36:39]
	v_mfma_f32_16x16x32_bf16 v[32:35], v[216:219], v[192:195], v[32:35]
	s_mov_b32 m0, s17
	v_lshl_add_u64 v[222:223], s[30:31], 0, v[128:129]
	s_barrier
	ds_read_b128 v[160:163], v143 offset:16384
	ds_read_b128 v[164:167], v143 offset:17408
	ds_read_b128 v[168:171], v143 offset:18432
	ds_read_b128 v[172:175], v143 offset:19456
	ds_read_b128 v[180:183], v143 offset:20480
	ds_read_b128 v[184:187], v143 offset:21504
	ds_read_b128 v[188:191], v143 offset:22528
	ds_read_b128 v[192:195], v143 offset:23552
	global_load_lds_dwordx4 v[222:223], off
	v_lshl_add_u64 v[224:225], s[30:31], 0, v[132:133]
	s_mov_b32 m0, s19
	s_nop 0
	global_load_lds_dwordx4 v[224:225], off
	s_barrier
	s_waitcnt lgkmcnt(0)
	v_mfma_f32_16x16x32_bf16 v[92:95], v[144:147], v[160:163], 0
	v_mfma_f32_16x16x32_bf16 v[88:91], v[152:155], v[160:163], 0
	v_mfma_f32_16x16x32_bf16 v[84:87], v[144:147], v[168:171], 0
	v_mfma_f32_16x16x32_bf16 v[80:83], v[152:155], v[168:171], 0
	v_mfma_f32_16x16x32_bf16 v[76:79], v[144:147], v[180:183], 0
	v_mfma_f32_16x16x32_bf16 v[68:71], v[152:155], v[180:183], 0
	v_mfma_f32_16x16x32_bf16 v[60:63], v[144:147], v[188:191], 0
	v_mfma_f32_16x16x32_bf16 v[52:55], v[152:155], v[188:191], 0
	v_mfma_f32_16x16x32_bf16 v[92:95], v[148:151], v[164:167], v[92:95]
	v_mfma_f32_16x16x32_bf16 v[88:91], v[156:159], v[164:167], v[88:91]
	v_mfma_f32_16x16x32_bf16 v[84:87], v[148:151], v[172:175], v[84:87]
	v_mfma_f32_16x16x32_bf16 v[80:83], v[156:159], v[172:175], v[80:83]
	v_mfma_f32_16x16x32_bf16 v[76:79], v[148:151], v[184:187], v[76:79]
	v_mfma_f32_16x16x32_bf16 v[68:71], v[156:159], v[184:187], v[68:71]
	v_mfma_f32_16x16x32_bf16 v[60:63], v[148:151], v[192:195], v[60:63]
	v_mfma_f32_16x16x32_bf16 v[52:55], v[156:159], v[192:195], v[52:55]
	s_barrier
	s_add_u32 s34, s42, s44
	s_addc_u32 s35, s43, 0
	s_add_i32 s29, s29, s48
	v_lshl_add_u64 v[226:227], s[34:35], 0, v[130:131]
	s_mov_b32 m0, s29
	v_lshl_add_u64 v[228:229], s[34:35], 0, v[134:135]
	global_load_lds_dwordx4 v[226:227], off
	s_add_i32 m0, s29, 0x2000
	s_nop 0
	global_load_lds_dwordx4 v[228:229], off
	s_waitcnt vmcnt(6)
	s_barrier
	v_mfma_f32_16x16x32_bf16 v[28:31], v[196:199], v[160:163], 0
	v_mfma_f32_16x16x32_bf16 v[24:27], v[212:215], v[160:163], 0
	v_mfma_f32_16x16x32_bf16 v[20:23], v[196:199], v[168:171], 0
	v_mfma_f32_16x16x32_bf16 v[16:19], v[212:215], v[168:171], 0
	v_mfma_f32_16x16x32_bf16 v[12:15], v[196:199], v[180:183], 0
	v_mfma_f32_16x16x32_bf16 v[8:11], v[212:215], v[180:183], 0
	v_mfma_f32_16x16x32_bf16 v[4:7], v[196:199], v[188:191], 0
	v_mfma_f32_16x16x32_bf16 v[0:3], v[212:215], v[188:191], 0
	v_mfma_f32_16x16x32_bf16 v[28:31], v[208:211], v[164:167], v[28:31]
	v_mfma_f32_16x16x32_bf16 v[24:27], v[216:219], v[164:167], v[24:27]
	v_mfma_f32_16x16x32_bf16 v[20:23], v[208:211], v[172:175], v[20:23]
	v_mfma_f32_16x16x32_bf16 v[16:19], v[216:219], v[172:175], v[16:19]
	v_mfma_f32_16x16x32_bf16 v[12:15], v[208:211], v[184:187], v[12:15]
	v_mfma_f32_16x16x32_bf16 v[8:11], v[216:219], v[184:187], v[8:11]
	v_mfma_f32_16x16x32_bf16 v[4:7], v[208:211], v[192:195], v[4:7]
	v_mfma_f32_16x16x32_bf16 v[0:3], v[216:219], v[192:195], v[0:3]
	s_add_i32 s29, 0, 0x18000
	v_add_u32_e32 v156, s29, v141
	s_barrier
	ds_read_b128 v[144:147], v156
	ds_read_b128 v[148:151], v156 offset:1024
	ds_read_b128 v[152:155], v156 offset:2048
	ds_read_b128 v[156:159], v156 offset:3072
	s_add_u32 s30, s30, s44
	s_addc_u32 s31, s31, 0
	s_mov_b32 m0, s51
	v_lshl_add_u64 v[196:197], s[30:31], 0, v[128:129]
	ds_read_b128 v[160:163], v143 offset:32768
	ds_read_b128 v[164:167], v143 offset:33792
	ds_read_b128 v[168:171], v143 offset:34816
	ds_read_b128 v[172:175], v143 offset:35840
	ds_read_b128 v[180:183], v143 offset:36864
	ds_read_b128 v[184:187], v143 offset:37888
	ds_read_b128 v[188:191], v143 offset:38912
	ds_read_b128 v[192:195], v143 offset:39936
	global_load_lds_dwordx4 v[196:197], off
	v_lshl_add_u64 v[196:197], s[30:31], 0, v[132:133]
	s_mov_b32 m0, s52
	s_nop 0
	global_load_lds_dwordx4 v[196:197], off
	s_waitcnt lgkmcnt(8)
	s_barrier
	s_waitcnt lgkmcnt(0)
	v_mfma_f32_16x16x32_bf16 v[124:127], v[144:147], v[160:163], v[124:127]
	v_mfma_f32_16x16x32_bf16 v[120:123], v[152:155], v[160:163], v[120:123]
	v_mfma_f32_16x16x32_bf16 v[116:119], v[144:147], v[168:171], v[116:119]
	v_mfma_f32_16x16x32_bf16 v[112:115], v[152:155], v[168:171], v[112:115]
	v_mfma_f32_16x16x32_bf16 v[108:111], v[144:147], v[180:183], v[108:111]
	v_mfma_f32_16x16x32_bf16 v[104:107], v[152:155], v[180:183], v[104:107]
	v_mfma_f32_16x16x32_bf16 v[100:103], v[144:147], v[188:191], v[100:103]
	v_mfma_f32_16x16x32_bf16 v[96:99], v[152:155], v[188:191], v[96:99]
	v_mfma_f32_16x16x32_bf16 v[124:127], v[148:151], v[164:167], v[124:127]
	v_mfma_f32_16x16x32_bf16 v[120:123], v[156:159], v[164:167], v[120:123]
	v_mfma_f32_16x16x32_bf16 v[116:119], v[148:151], v[172:175], v[116:119]
	v_mfma_f32_16x16x32_bf16 v[112:115], v[156:159], v[172:175], v[112:115]
	v_mfma_f32_16x16x32_bf16 v[108:111], v[148:151], v[184:187], v[108:111]
	v_mfma_f32_16x16x32_bf16 v[104:107], v[156:159], v[184:187], v[104:107]
	v_mfma_f32_16x16x32_bf16 v[100:103], v[148:151], v[192:195], v[100:103]
	v_mfma_f32_16x16x32_bf16 v[96:99], v[156:159], v[192:195], v[96:99]
	s_barrier
	s_add_i32 s30, 0, 0x1c000
	s_add_i32 s29, s29, s48
	v_add_u32_e32 v176, s30, v141
	v_lshl_add_u64 v[200:201], v[200:201], 0, s[40:41]
	s_mov_b32 m0, s29
	ds_read_b128 v[196:199], v176
	ds_read_b128 v[208:211], v176 offset:1024
	ds_read_b128 v[212:215], v176 offset:2048
	ds_read_b128 v[216:219], v176 offset:3072
	global_load_lds_dwordx4 v[200:201], off
	v_lshl_add_u64 v[200:201], v[220:221], 0, s[40:41]
	s_add_i32 m0, s29, 0x2000
	s_nop 0
	global_load_lds_dwordx4 v[200:201], off
	s_barrier
	s_waitcnt lgkmcnt(0)
	v_mfma_f32_16x16x32_bf16 v[72:75], v[196:199], v[160:163], v[72:75]
	v_mfma_f32_16x16x32_bf16 v[64:67], v[212:215], v[160:163], v[64:67]
	v_mfma_f32_16x16x32_bf16 v[56:59], v[196:199], v[168:171], v[56:59]
	v_mfma_f32_16x16x32_bf16 v[48:51], v[212:215], v[168:171], v[48:51]
	v_mfma_f32_16x16x32_bf16 v[44:47], v[196:199], v[180:183], v[44:47]
	v_mfma_f32_16x16x32_bf16 v[40:43], v[212:215], v[180:183], v[40:43]
	v_mfma_f32_16x16x32_bf16 v[36:39], v[196:199], v[188:191], v[36:39]
	v_mfma_f32_16x16x32_bf16 v[32:35], v[212:215], v[188:191], v[32:35]
	v_mfma_f32_16x16x32_bf16 v[72:75], v[208:211], v[164:167], v[72:75]
	v_mfma_f32_16x16x32_bf16 v[64:67], v[216:219], v[164:167], v[64:67]
	v_mfma_f32_16x16x32_bf16 v[56:59], v[208:211], v[172:175], v[56:59]
	v_mfma_f32_16x16x32_bf16 v[48:51], v[216:219], v[172:175], v[48:51]
	v_mfma_f32_16x16x32_bf16 v[44:47], v[208:211], v[184:187], v[44:47]
	v_mfma_f32_16x16x32_bf16 v[40:43], v[216:219], v[184:187], v[40:43]
	v_mfma_f32_16x16x32_bf16 v[36:39], v[208:211], v[192:195], v[36:39]
	v_mfma_f32_16x16x32_bf16 v[32:35], v[216:219], v[192:195], v[32:35]
	s_mov_b32 m0, s56
	v_lshl_add_u64 v[200:201], v[222:223], 0, s[40:41]
	s_barrier
	ds_read_b128 v[160:163], v143 offset:49152
	ds_read_b128 v[164:167], v143 offset:50176
	ds_read_b128 v[168:171], v143 offset:51200
	ds_read_b128 v[172:175], v143 offset:52224
	ds_read_b128 v[180:183], v143 offset:53248
	ds_read_b128 v[184:187], v143 offset:54272
	ds_read_b128 v[188:191], v143 offset:55296
	ds_read_b128 v[192:195], v143 offset:56320
	global_load_lds_dwordx4 v[200:201], off
	v_lshl_add_u64 v[200:201], v[224:225], 0, s[40:41]
	s_mov_b32 m0, s57
	s_nop 0
	global_load_lds_dwordx4 v[200:201], off
	s_barrier
	s_waitcnt lgkmcnt(0)
	v_mfma_f32_16x16x32_bf16 v[92:95], v[144:147], v[160:163], v[92:95]
	v_mfma_f32_16x16x32_bf16 v[88:91], v[152:155], v[160:163], v[88:91]
	v_mfma_f32_16x16x32_bf16 v[84:87], v[144:147], v[168:171], v[84:87]
	v_mfma_f32_16x16x32_bf16 v[80:83], v[152:155], v[168:171], v[80:83]
	v_mfma_f32_16x16x32_bf16 v[76:79], v[144:147], v[180:183], v[76:79]
	v_mfma_f32_16x16x32_bf16 v[68:71], v[152:155], v[180:183], v[68:71]
	v_mfma_f32_16x16x32_bf16 v[60:63], v[144:147], v[188:191], v[60:63]
	v_mfma_f32_16x16x32_bf16 v[52:55], v[152:155], v[188:191], v[52:55]
	v_mfma_f32_16x16x32_bf16 v[92:95], v[148:151], v[164:167], v[92:95]
	v_mfma_f32_16x16x32_bf16 v[88:91], v[156:159], v[164:167], v[88:91]
	v_mfma_f32_16x16x32_bf16 v[84:87], v[148:151], v[172:175], v[84:87]
	v_mfma_f32_16x16x32_bf16 v[80:83], v[156:159], v[172:175], v[80:83]
	v_mfma_f32_16x16x32_bf16 v[76:79], v[148:151], v[184:187], v[76:79]
	v_mfma_f32_16x16x32_bf16 v[68:71], v[156:159], v[184:187], v[68:71]
	v_mfma_f32_16x16x32_bf16 v[60:63], v[148:151], v[192:195], v[60:63]
	v_mfma_f32_16x16x32_bf16 v[52:55], v[156:159], v[192:195], v[52:55]
	s_barrier
	s_add_i32 s29, s30, s48
	v_lshl_add_u64 v[144:145], v[226:227], 0, s[40:41]
	s_mov_b32 m0, s29
	s_nop 0
	global_load_lds_dwordx4 v[144:145], off
	v_lshl_add_u64 v[144:145], v[228:229], 0, s[40:41]
	s_add_i32 m0, s29, 0x2000
	s_nop 0
	global_load_lds_dwordx4 v[144:145], off
	s_waitcnt vmcnt(6)
	s_barrier
	v_mfma_f32_16x16x32_bf16 v[28:31], v[196:199], v[160:163], v[28:31]
	v_mfma_f32_16x16x32_bf16 v[24:27], v[212:215], v[160:163], v[24:27]
	v_mfma_f32_16x16x32_bf16 v[20:23], v[196:199], v[168:171], v[20:23]
	v_mfma_f32_16x16x32_bf16 v[16:19], v[212:215], v[168:171], v[16:19]
	v_mfma_f32_16x16x32_bf16 v[12:15], v[196:199], v[180:183], v[12:15]
	v_mfma_f32_16x16x32_bf16 v[8:11], v[212:215], v[180:183], v[8:11]
	v_mfma_f32_16x16x32_bf16 v[4:7], v[196:199], v[188:191], v[4:7]
	v_mfma_f32_16x16x32_bf16 v[0:3], v[212:215], v[188:191], v[0:3]
	v_mfma_f32_16x16x32_bf16 v[28:31], v[208:211], v[164:167], v[28:31]
	v_mfma_f32_16x16x32_bf16 v[24:27], v[216:219], v[164:167], v[24:27]
	v_mfma_f32_16x16x32_bf16 v[20:23], v[208:211], v[172:175], v[20:23]
	v_mfma_f32_16x16x32_bf16 v[16:19], v[216:219], v[172:175], v[16:19]
	v_mfma_f32_16x16x32_bf16 v[12:15], v[208:211], v[184:187], v[12:15]
	v_mfma_f32_16x16x32_bf16 v[8:11], v[216:219], v[184:187], v[8:11]
	v_mfma_f32_16x16x32_bf16 v[4:7], v[208:211], v[192:195], v[4:7]
	v_mfma_f32_16x16x32_bf16 v[0:3], v[216:219], v[192:195], v[0:3]
	s_add_u32 s26, s26, 0x100
	s_addc_u32 s27, s27, 0
	s_add_u32 s13, s13, 0x100
	s_addc_u32 s15, s15, 0
	s_cmp_ge_u32 s60, s55
	s_mov_b32 s30, s60
	s_barrier

.LBB0_655:
	v_mov_b64_e32 v[0:1], s[2:3]
	s_ashr_i32 s9, s8, 31
	v_cmp_lt_i64_e32 vcc, s[10:11], v[0:1]
	s_lshl_b64 s[10:11], s[8:9], 20
	v_readlane_b32 s12, v255, 26
	v_readlane_b32 s13, v255, 27
	s_add_u32 s10, s12, s10
	s_addc_u32 s11, s13, s11
	s_and_b64 s[12:13], vcc, exec
	s_cselect_b32 s9, s11, s21
	s_cselect_b32 s15, s10, s20
	s_ashr_i32 s5, s4, 31
	s_lshl_b64 s[12:13], s[4:5], 20
	s_add_u32 s12, s26, s12
	s_addc_u32 s13, s27, s13
	s_and_b64 s[24:25], vcc, exec
	s_cselect_b32 s5, s13, s19
	s_cselect_b32 s17, s12, s18
	s_add_u32 s44, s18, 0x100
	s_addc_u32 s53, s19, 0
	s_add_u32 s18, s20, 0x80080
	s_addc_u32 s19, s21, 0
	s_mov_b32 s54, -2
	s_add_u32 s20, s18, 0xfff80080
	s_addc_u32 s21, s19, -1
	s_add_i32 s34, 0, 0x10000
	v_add_u32_e32 v152, s34, v174
	ds_read_b128 v[140:143], v152
	ds_read_b128 v[144:147], v152 offset:1024
	ds_read_b128 v[148:151], v152 offset:2048
	ds_read_b128 v[152:155], v152 offset:3072
	s_cmp_eq_u32 s54, 28
	s_cselect_b32 s25, s9, s21
	s_cselect_b32 s24, s15, s20
	s_cselect_b32 s21, s5, s53
	s_cselect_b32 s20, s17, s44
	v_lshl_add_u64 v[180:181], s[18:19], 0, v[136:137]
	s_add_i32 m0, s30, 0xc000
	ds_read_b128 v[156:159], v189
	ds_read_b128 v[160:163], v189 offset:1024
	ds_read_b128 v[164:167], v189 offset:2048
	ds_read_b128 v[168:171], v189 offset:3072
	ds_read_b128 v[190:193], v189 offset:4096
	ds_read_b128 v[194:197], v189 offset:5120
	ds_read_b128 v[198:201], v189 offset:6144
	ds_read_b128 v[208:211], v189 offset:7168
	global_load_lds_dwordx4 v[180:181], off
	v_lshl_add_u64 v[180:181], s[18:19], 0, v[138:139]
	s_add_i32 m0, s30, 0xe000
	s_nop 0
	global_load_lds_dwordx4 v[180:181], off
	s_waitcnt lgkmcnt(8)
	s_barrier
	s_waitcnt lgkmcnt(0)
	v_mfma_f32_16x16x32_bf16 v[124:127], v[140:143], v[156:159], 0
	v_mfma_f32_16x16x32_bf16 v[120:123], v[148:151], v[156:159], 0
	v_mfma_f32_16x16x32_bf16 v[108:111], v[140:143], v[164:167], 0
	v_mfma_f32_16x16x32_bf16 v[104:107], v[148:151], v[164:167], 0
	v_mfma_f32_16x16x32_bf16 v[92:95], v[140:143], v[190:193], 0
	v_mfma_f32_16x16x32_bf16 v[88:91], v[148:151], v[190:193], 0
	v_mfma_f32_16x16x32_bf16 v[76:79], v[140:143], v[198:201], 0
	v_mfma_f32_16x16x32_bf16 v[72:75], v[148:151], v[198:201], 0
	v_mfma_f32_16x16x32_bf16 v[124:127], v[144:147], v[160:163], v[124:127]
	v_mfma_f32_16x16x32_bf16 v[120:123], v[152:155], v[160:163], v[120:123]
	v_mfma_f32_16x16x32_bf16 v[108:111], v[144:147], v[168:171], v[108:111]
	v_mfma_f32_16x16x32_bf16 v[104:107], v[152:155], v[168:171], v[104:107]
	v_mfma_f32_16x16x32_bf16 v[92:95], v[144:147], v[194:197], v[92:95]
	v_mfma_f32_16x16x32_bf16 v[88:91], v[152:155], v[194:197], v[88:91]
	v_mfma_f32_16x16x32_bf16 v[76:79], v[144:147], v[208:211], v[76:79]
	v_mfma_f32_16x16x32_bf16 v[72:75], v[152:155], v[208:211], v[72:75]
	s_barrier
	s_add_i32 s35, 0, 0x14000
	s_add_i32 s34, s34, s28
	v_add_u32_e32 v176, s35, v174
	v_lshl_add_u64 v[180:181], s[20:21], 0, v[130:131]
	s_mov_b32 m0, s34
	ds_read_b128 v[212:215], v176
	ds_read_b128 v[216:219], v176 offset:1024
	ds_read_b128 v[220:223], v176 offset:2048
	ds_read_b128 v[224:227], v176 offset:3072
	global_load_lds_dwordx4 v[180:181], off
	v_lshl_add_u64 v[228:229], s[20:21], 0, v[134:135]
	s_add_i32 m0, s34, 0x2000
	s_nop 0
	global_load_lds_dwordx4 v[228:229], off
	s_barrier
	s_waitcnt lgkmcnt(0)
	v_mfma_f32_16x16x32_bf16 v[116:119], v[212:215], v[156:159], 0
	v_mfma_f32_16x16x32_bf16 v[112:115], v[220:223], v[156:159], 0
	v_mfma_f32_16x16x32_bf16 v[100:103], v[212:215], v[164:167], 0
	v_mfma_f32_16x16x32_bf16 v[96:99], v[220:223], v[164:167], 0
	v_mfma_f32_16x16x32_bf16 v[84:87], v[212:215], v[190:193], 0
	v_mfma_f32_16x16x32_bf16 v[80:83], v[220:223], v[190:193], 0
	v_mfma_f32_16x16x32_bf16 v[68:71], v[212:215], v[198:201], 0
	v_mfma_f32_16x16x32_bf16 v[64:67], v[220:223], v[198:201], 0
	v_mfma_f32_16x16x32_bf16 v[116:119], v[216:219], v[160:163], v[116:119]
	v_mfma_f32_16x16x32_bf16 v[112:115], v[224:227], v[160:163], v[112:115]
	v_mfma_f32_16x16x32_bf16 v[100:103], v[216:219], v[168:171], v[100:103]
	v_mfma_f32_16x16x32_bf16 v[96:99], v[224:227], v[168:171], v[96:99]
	v_mfma_f32_16x16x32_bf16 v[84:87], v[216:219], v[194:197], v[84:87]
	v_mfma_f32_16x16x32_bf16 v[80:83], v[224:227], v[194:197], v[80:83]
	v_mfma_f32_16x16x32_bf16 v[68:71], v[216:219], v[208:211], v[68:71]
	v_mfma_f32_16x16x32_bf16 v[64:67], v[224:227], v[208:211], v[64:67]
	s_mov_b32 m0, s30
	v_lshl_add_u64 v[230:231], s[24:25], 0, v[128:129]
	s_barrier
	ds_read_b128 v[156:159], v189 offset:16384
	ds_read_b128 v[160:163], v189 offset:17408
	ds_read_b128 v[164:167], v189 offset:18432
	ds_read_b128 v[168:171], v189 offset:19456
	ds_read_b128 v[190:193], v189 offset:20480
	ds_read_b128 v[194:197], v189 offset:21504
	ds_read_b128 v[198:201], v189 offset:22528
	ds_read_b128 v[208:211], v189 offset:23552
	global_load_lds_dwordx4 v[230:231], off
	v_lshl_add_u64 v[232:233], s[24:25], 0, v[132:133]
	s_mov_b32 m0, s31
	s_nop 0
	global_load_lds_dwordx4 v[232:233], off
	s_barrier
	s_waitcnt lgkmcnt(0)
	v_mfma_f32_16x16x32_bf16 v[60:63], v[140:143], v[156:159], 0
	v_mfma_f32_16x16x32_bf16 v[56:59], v[148:151], v[156:159], 0
	v_mfma_f32_16x16x32_bf16 v[44:47], v[140:143], v[164:167], 0
	v_mfma_f32_16x16x32_bf16 v[40:43], v[148:151], v[164:167], 0
	v_mfma_f32_16x16x32_bf16 v[28:31], v[140:143], v[190:193], 0
	v_mfma_f32_16x16x32_bf16 v[24:27], v[148:151], v[190:193], 0
	v_mfma_f32_16x16x32_bf16 v[12:15], v[140:143], v[198:201], 0
	v_mfma_f32_16x16x32_bf16 v[8:11], v[148:151], v[198:201], 0
	v_mfma_f32_16x16x32_bf16 v[60:63], v[144:147], v[160:163], v[60:63]
	v_mfma_f32_16x16x32_bf16 v[56:59], v[152:155], v[160:163], v[56:59]
	v_mfma_f32_16x16x32_bf16 v[44:47], v[144:147], v[168:171], v[44:47]
	v_mfma_f32_16x16x32_bf16 v[40:43], v[152:155], v[168:171], v[40:43]
	v_mfma_f32_16x16x32_bf16 v[28:31], v[144:147], v[194:197], v[28:31]
	v_mfma_f32_16x16x32_bf16 v[24:27], v[152:155], v[194:197], v[24:27]
	v_mfma_f32_16x16x32_bf16 v[12:15], v[144:147], v[208:211], v[12:15]
	v_mfma_f32_16x16x32_bf16 v[8:11], v[152:155], v[208:211], v[8:11]
	s_barrier
	s_add_u32 s56, s20, 0x80000
	s_addc_u32 s57, s21, 0
	s_add_i32 s34, s35, s28
	v_lshl_add_u64 v[140:141], s[56:57], 0, v[130:131]
	s_mov_b32 m0, s34
	s_nop 0
	global_load_lds_dwordx4 v[140:141], off
	v_lshl_add_u64 v[140:141], s[56:57], 0, v[134:135]
	s_add_i32 m0, s34, 0x2000
	s_nop 0
	global_load_lds_dwordx4 v[140:141], off
	s_waitcnt vmcnt(6)
	s_barrier
	v_mfma_f32_16x16x32_bf16 v[52:55], v[212:215], v[156:159], 0
	v_mfma_f32_16x16x32_bf16 v[48:51], v[220:223], v[156:159], 0
	v_mfma_f32_16x16x32_bf16 v[36:39], v[212:215], v[164:167], 0
	v_mfma_f32_16x16x32_bf16 v[32:35], v[220:223], v[164:167], 0
	v_mfma_f32_16x16x32_bf16 v[20:23], v[212:215], v[190:193], 0
	v_mfma_f32_16x16x32_bf16 v[16:19], v[220:223], v[190:193], 0
	v_mfma_f32_16x16x32_bf16 v[4:7], v[212:215], v[198:201], 0
	v_mfma_f32_16x16x32_bf16 v[0:3], v[220:223], v[198:201], 0
	v_mfma_f32_16x16x32_bf16 v[52:55], v[216:219], v[160:163], v[52:55]
	v_mfma_f32_16x16x32_bf16 v[48:51], v[224:227], v[160:163], v[48:51]
	v_mfma_f32_16x16x32_bf16 v[36:39], v[216:219], v[168:171], v[36:39]
	v_mfma_f32_16x16x32_bf16 v[32:35], v[224:227], v[168:171], v[32:35]
	v_mfma_f32_16x16x32_bf16 v[20:23], v[216:219], v[194:197], v[20:23]
	v_mfma_f32_16x16x32_bf16 v[16:19], v[224:227], v[194:197], v[16:19]
	v_mfma_f32_16x16x32_bf16 v[4:7], v[216:219], v[208:211], v[4:7]
	v_mfma_f32_16x16x32_bf16 v[0:3], v[224:227], v[208:211], v[0:3]
	s_add_i32 s34, 0, 0x18000
	v_add_u32_e32 v152, s34, v174
	s_barrier
	ds_read_b128 v[140:143], v152
	ds_read_b128 v[144:147], v152 offset:1024
	ds_read_b128 v[148:151], v152 offset:2048
	ds_read_b128 v[152:155], v152 offset:3072
	s_add_u32 s24, s24, 0x80000
	s_addc_u32 s25, s25, 0
	s_mov_b32 m0, s33
	v_lshl_add_u64 v[212:213], s[24:25], 0, v[128:129]
	ds_read_b128 v[156:159], v189 offset:32768
	ds_read_b128 v[160:163], v189 offset:33792
	ds_read_b128 v[164:167], v189 offset:34816
	ds_read_b128 v[168:171], v189 offset:35840
	ds_read_b128 v[190:193], v189 offset:36864
	ds_read_b128 v[194:197], v189 offset:37888
	ds_read_b128 v[198:201], v189 offset:38912
	ds_read_b128 v[208:211], v189 offset:39936
	global_load_lds_dwordx4 v[212:213], off
	v_lshl_add_u64 v[212:213], s[24:25], 0, v[132:133]
	s_mov_b32 m0, s37
	s_nop 0
	global_load_lds_dwordx4 v[212:213], off
	s_waitcnt lgkmcnt(8)
	s_barrier
	s_waitcnt lgkmcnt(0)
	v_mfma_f32_16x16x32_bf16 v[124:127], v[140:143], v[156:159], v[124:127]
	v_mfma_f32_16x16x32_bf16 v[120:123], v[148:151], v[156:159], v[120:123]
	v_mfma_f32_16x16x32_bf16 v[108:111], v[140:143], v[164:167], v[108:111]
	v_mfma_f32_16x16x32_bf16 v[104:107], v[148:151], v[164:167], v[104:107]
	v_mfma_f32_16x16x32_bf16 v[92:95], v[140:143], v[190:193], v[92:95]
	v_mfma_f32_16x16x32_bf16 v[88:91], v[148:151], v[190:193], v[88:91]
	v_mfma_f32_16x16x32_bf16 v[76:79], v[140:143], v[198:201], v[76:79]
	v_mfma_f32_16x16x32_bf16 v[72:75], v[148:151], v[198:201], v[72:75]
	v_mfma_f32_16x16x32_bf16 v[124:127], v[144:147], v[160:163], v[124:127]
	v_mfma_f32_16x16x32_bf16 v[120:123], v[152:155], v[160:163], v[120:123]
	v_mfma_f32_16x16x32_bf16 v[108:111], v[144:147], v[168:171], v[108:111]
	v_mfma_f32_16x16x32_bf16 v[104:107], v[152:155], v[168:171], v[104:107]
	v_mfma_f32_16x16x32_bf16 v[92:95], v[144:147], v[194:197], v[92:95]
	v_mfma_f32_16x16x32_bf16 v[88:91], v[152:155], v[194:197], v[88:91]
	v_mfma_f32_16x16x32_bf16 v[76:79], v[144:147], v[208:211], v[76:79]
	v_mfma_f32_16x16x32_bf16 v[72:75], v[152:155], v[208:211], v[72:75]
	s_barrier
	s_add_i32 s24, 0, 0x1c000
	s_add_i32 s25, s34, s28
	v_add_u32_e32 v176, s24, v174
	v_lshl_add_u64 v[180:181], v[180:181], 0, s[40:41]
	s_mov_b32 m0, s25
	ds_read_b128 v[212:215], v176
	ds_read_b128 v[216:219], v176 offset:1024
	ds_read_b128 v[220:223], v176 offset:2048
	ds_read_b128 v[224:227], v176 offset:3072
	global_load_lds_dwordx4 v[180:181], off
	v_lshl_add_u64 v[180:181], v[228:229], 0, s[40:41]
	s_add_i32 m0, s25, 0x2000
	s_nop 0
	global_load_lds_dwordx4 v[180:181], off
	s_barrier
	s_waitcnt lgkmcnt(0)
	v_mfma_f32_16x16x32_bf16 v[116:119], v[212:215], v[156:159], v[116:119]
	v_mfma_f32_16x16x32_bf16 v[112:115], v[220:223], v[156:159], v[112:115]
	v_mfma_f32_16x16x32_bf16 v[100:103], v[212:215], v[164:167], v[100:103]
	v_mfma_f32_16x16x32_bf16 v[96:99], v[220:223], v[164:167], v[96:99]
	v_mfma_f32_16x16x32_bf16 v[84:87], v[212:215], v[190:193], v[84:87]
	v_mfma_f32_16x16x32_bf16 v[80:83], v[220:223], v[190:193], v[80:83]
	v_mfma_f32_16x16x32_bf16 v[68:71], v[212:215], v[198:201], v[68:71]
	v_mfma_f32_16x16x32_bf16 v[64:67], v[220:223], v[198:201], v[64:67]
	v_mfma_f32_16x16x32_bf16 v[116:119], v[216:219], v[160:163], v[116:119]
	v_mfma_f32_16x16x32_bf16 v[112:115], v[224:227], v[160:163], v[112:115]
	v_mfma_f32_16x16x32_bf16 v[100:103], v[216:219], v[168:171], v[100:103]
	v_mfma_f32_16x16x32_bf16 v[96:99], v[224:227], v[168:171], v[96:99]
	v_mfma_f32_16x16x32_bf16 v[84:87], v[216:219], v[194:197], v[84:87]
	v_mfma_f32_16x16x32_bf16 v[80:83], v[224:227], v[194:197], v[80:83]
	v_mfma_f32_16x16x32_bf16 v[68:71], v[216:219], v[208:211], v[68:71]
	v_mfma_f32_16x16x32_bf16 v[64:67], v[224:227], v[208:211], v[64:67]
	s_mov_b32 m0, s47
	v_lshl_add_u64 v[180:181], v[230:231], 0, s[40:41]
	s_barrier
	ds_read_b128 v[156:159], v189 offset:49152
	ds_read_b128 v[160:163], v189 offset:50176
	ds_read_b128 v[164:167], v189 offset:51200
	ds_read_b128 v[168:171], v189 offset:52224
	ds_read_b128 v[190:193], v189 offset:53248
	ds_read_b128 v[194:197], v189 offset:54272
	ds_read_b128 v[198:201], v189 offset:55296
	ds_read_b128 v[208:211], v189 offset:56320
	global_load_lds_dwordx4 v[180:181], off
	v_lshl_add_u64 v[180:181], v[232:233], 0, s[40:41]
	s_mov_b32 m0, s48
	s_nop 0
	global_load_lds_dwordx4 v[180:181], off
	s_barrier
	s_waitcnt lgkmcnt(0)
	v_mfma_f32_16x16x32_bf16 v[60:63], v[140:143], v[156:159], v[60:63]
	v_mfma_f32_16x16x32_bf16 v[56:59], v[148:151], v[156:159], v[56:59]
	v_mfma_f32_16x16x32_bf16 v[44:47], v[140:143], v[164:167], v[44:47]
	v_mfma_f32_16x16x32_bf16 v[40:43], v[148:151], v[164:167], v[40:43]
	v_mfma_f32_16x16x32_bf16 v[28:31], v[140:143], v[190:193], v[28:31]
	v_mfma_f32_16x16x32_bf16 v[24:27], v[148:151], v[190:193], v[24:27]
	v_mfma_f32_16x16x32_bf16 v[12:15], v[140:143], v[198:201], v[12:15]
	v_mfma_f32_16x16x32_bf16 v[8:11], v[148:151], v[198:201], v[8:11]
	v_mfma_f32_16x16x32_bf16 v[60:63], v[144:147], v[160:163], v[60:63]
	v_mfma_f32_16x16x32_bf16 v[56:59], v[152:155], v[160:163], v[56:59]
	v_mfma_f32_16x16x32_bf16 v[44:47], v[144:147], v[168:171], v[44:47]
	v_mfma_f32_16x16x32_bf16 v[40:43], v[152:155], v[168:171], v[40:43]
	v_mfma_f32_16x16x32_bf16 v[28:31], v[144:147], v[194:197], v[28:31]
	v_mfma_f32_16x16x32_bf16 v[24:27], v[152:155], v[194:197], v[24:27]
	v_mfma_f32_16x16x32_bf16 v[12:15], v[144:147], v[208:211], v[12:15]
	v_mfma_f32_16x16x32_bf16 v[8:11], v[152:155], v[208:211], v[8:11]
	s_barrier
	s_add_u32 s20, s20, 0x80080
	s_addc_u32 s21, s21, 0
	s_add_i32 s24, s24, s28
	v_lshl_add_u64 v[140:141], s[20:21], 0, v[130:131]
	s_mov_b32 m0, s24
	s_nop 0
	global_load_lds_dwordx4 v[140:141], off
	v_lshl_add_u64 v[140:141], s[20:21], 0, v[134:135]
	s_add_i32 m0, s24, 0x2000
	s_nop 0
	global_load_lds_dwordx4 v[140:141], off
	s_waitcnt vmcnt(6)
	s_barrier
	v_mfma_f32_16x16x32_bf16 v[52:55], v[212:215], v[156:159], v[52:55]
	v_mfma_f32_16x16x32_bf16 v[48:51], v[220:223], v[156:159], v[48:51]
	v_mfma_f32_16x16x32_bf16 v[36:39], v[212:215], v[164:167], v[36:39]
	v_mfma_f32_16x16x32_bf16 v[32:35], v[220:223], v[164:167], v[32:35]
	v_mfma_f32_16x16x32_bf16 v[20:23], v[212:215], v[190:193], v[20:23]
	v_mfma_f32_16x16x32_bf16 v[16:19], v[220:223], v[190:193], v[16:19]
	v_mfma_f32_16x16x32_bf16 v[4:7], v[212:215], v[198:201], v[4:7]
	v_mfma_f32_16x16x32_bf16 v[0:3], v[220:223], v[198:201], v[0:3]
	v_mfma_f32_16x16x32_bf16 v[52:55], v[216:219], v[160:163], v[52:55]
	v_mfma_f32_16x16x32_bf16 v[48:51], v[224:227], v[160:163], v[48:51]
	v_mfma_f32_16x16x32_bf16 v[36:39], v[216:219], v[168:171], v[36:39]
	v_mfma_f32_16x16x32_bf16 v[32:35], v[224:227], v[168:171], v[32:35]
	v_mfma_f32_16x16x32_bf16 v[20:23], v[216:219], v[194:197], v[20:23]
	v_mfma_f32_16x16x32_bf16 v[16:19], v[224:227], v[194:197], v[16:19]
	v_mfma_f32_16x16x32_bf16 v[4:7], v[216:219], v[208:211], v[4:7]
	v_mfma_f32_16x16x32_bf16 v[0:3], v[224:227], v[208:211], v[0:3]
	s_add_i32 s54, s54, 2
	s_add_u32 s44, s44, 0x100
	s_addc_u32 s53, s53, 0
	s_add_u32 s18, s18, 0x100
	s_addc_u32 s19, s19, 0
	s_cmp_gt_u32 s54, 29
	s_barrier
